# W_in epilogue: both rope-table load pairs of a row block issued together (second pair staged in spare registers)
# baseline (speedup 1.0000x reference)
;     __device__ __forceinline__ void operator()(const f32x4 (&acc)[2][2][4][2], const Unit& u, int wr, int wc, int fr, int fq) const {
;     ...
;                     if (lat && (isq || isk)) {
; #pragma unroll
;                         for (int bj = 0; bj < 2; ++bj) {
;                             const int p = bj == 0 ? (t >> 6) : 128 + (t & 63);
;                             const f32x4 cs0 = *(const f32x4*)(ROPE + (p * 16 + 4 * fq) * 2), cs1 = *(const f32x4*)(ROPE + (p * 16 + 4 * fq) * 2 + 4);
;                             const f32x4 cv = {cs0[0], cs0[2], cs1[0], cs1[2]}, sv = {cs0[1], cs0[3], cs1[1], cs1[3]};
;                             const f32x4 a = v[bj][0], bb = v[bj][1];
;                             v[bj][0] = a * cv - bb * sv; v[bj][1] = bb * cv + a * sv;
;                         }
.LBB0_176:
	s_and_b64 s[14:15], s[10:11], s[14:15]
	v_cndmask_b32_e64 v160, 0, 1, s[14:15]
	s_andn2_b64 vcc, exec, s[14:15]
	v_readlane_b32 s14, v255, 12
	v_cmp_ne_u32_e64 s[10:11], 1, v160
	s_add_i32 s50, s50, s14
	s_cbranch_vccnz .LBB0_178
	s_ashr_i32 s14, s50, 1
	v_or_b32_e32 v160, s14, v230
	v_readlane_b32 s14, v254, 41
	v_ashrrev_i32_e32 v161, 31, v160
	v_readlane_b32 s15, v254, 42
	s_nop 1
	v_lshl_add_u64 v[160:161], v[160:161], 2, s[14:15]
	global_load_dwordx4 v[210:213], v[160:161], off
	global_load_dwordx4 v[218:221], v[160:161], off offset:16
	global_load_dwordx4 v[240:243], v[200:201], off
	global_load_dwordx4 v[244:247], v[200:201], off offset:16
	s_waitcnt vmcnt(2)
	v_mov_b32_e32 v214, v211
	v_mov_b32_e32 v215, v213
	v_mov_b32_e32 v226, v219
	v_mov_b32_e32 v227, v221
	v_mov_b32_e32 v219, v220
	v_mov_b32_e32 v211, v212
	v_pk_mul_f32 v[160:161], v[144:145], v[214:215]
	v_pk_mul_f32 v[162:163], v[146:147], v[226:227]
	v_pk_mul_f32 v[144:145], v[144:145], v[210:211]
	v_pk_mul_f32 v[146:147], v[146:147], v[218:219]
	v_pk_fma_f32 v[162:163], v[158:159], v[218:219], v[162:163] neg_lo:[0,0,1] neg_hi:[0,0,1]
	v_pk_fma_f32 v[160:161], v[156:157], v[210:211], v[160:161] neg_lo:[0,0,1] neg_hi:[0,0,1]
	v_pk_fma_f32 v[146:147], v[158:159], v[226:227], v[146:147]
	v_pk_fma_f32 v[144:145], v[156:157], v[214:215], v[144:145]
	s_waitcnt vmcnt(0)
	v_mov_b64_e32 v[156:157], v[240:241]
	v_mov_b64_e32 v[158:159], v[242:243]
	v_mov_b64_e32 v[210:211], v[244:245]
	v_mov_b64_e32 v[212:213], v[246:247]
	s_waitcnt vmcnt(1)
	v_mov_b32_e32 v220, v157
	v_mov_b32_e32 v221, v159
	s_waitcnt vmcnt(0)
	v_mov_b32_e32 v218, v211
	v_mov_b32_e32 v219, v213
	v_pk_mul_f32 v[226:227], v[148:149], v[220:221]
	v_mov_b32_e32 v211, v212
	v_mov_b32_e32 v157, v158
	v_pk_mul_f32 v[214:215], v[150:151], v[218:219]
	v_pk_fma_f32 v[212:213], v[152:153], v[156:157], v[226:227] neg_lo:[0,0,1] neg_hi:[0,0,1]
	v_pk_mul_f32 v[150:151], v[150:151], v[210:211]
	v_pk_mul_f32 v[148:149], v[148:149], v[156:157]
	v_pk_fma_f32 v[214:215], v[154:155], v[210:211], v[214:215] neg_lo:[0,0,1] neg_hi:[0,0,1]
	v_pk_fma_f32 v[150:151], v[154:155], v[218:219], v[150:151]
	v_pk_fma_f32 v[148:149], v[152:153], v[220:221], v[148:149]
	v_mov_b64_e32 v[152:153], v[212:213]
	v_mov_b64_e32 v[156:157], v[160:161]
	v_mov_b64_e32 v[154:155], v[214:215]
	v_mov_b64_e32 v[158:159], v[162:163]

;     __device__ __forceinline__ void operator()(const f32x4 (&acc)[2][2][4][2], const Unit& u, int wr, int wc, int fr, int fq) const {
;     ...
;                     if (lat && (isq || isk)) {
; #pragma unroll
;                         for (int bj = 0; bj < 2; ++bj) {
;                             const int p = bj == 0 ? (t >> 6) : 128 + (t & 63);
;                             const f32x4 cs0 = *(const f32x4*)(ROPE + (p * 16 + 4 * fq) * 2), cs1 = *(const f32x4*)(ROPE + (p * 16 + 4 * fq) * 2 + 4);
;                             const f32x4 cv = {cs0[0], cs0[2], cs1[0], cs1[2]}, sv = {cs0[1], cs0[3], cs1[1], cs1[3]};
;                             const f32x4 a = v[bj][0], bb = v[bj][1];
;                             v[bj][0] = a * cv - bb * sv; v[bj][1] = bb * cv + a * sv;
;                         }
.LBB0_188:
	s_and_b64 vcc, exec, s[10:11]
	s_cbranch_vccnz .LBB0_190
	s_ashr_i32 s12, s50, 1
	v_or_b32_e32 v160, s12, v230
	v_readlane_b32 s12, v254, 41
	v_ashrrev_i32_e32 v161, 31, v160
	v_readlane_b32 s13, v254, 42
	s_nop 1
	v_lshl_add_u64 v[160:161], v[160:161], 2, s[12:13]
	global_load_dwordx4 v[218:221], v[160:161], off
	global_load_dwordx4 v[234:237], v[160:161], off offset:16
	global_load_dwordx4 v[240:243], v[202:203], off
	global_load_dwordx4 v[244:247], v[202:203], off offset:16
	s_waitcnt vmcnt(2)
	v_mov_b32_e32 v226, v219
	v_mov_b32_e32 v227, v221
	v_mov_b32_e32 v228, v235
	v_mov_b32_e32 v229, v237
	v_mov_b32_e32 v235, v236
	v_mov_b32_e32 v219, v220
	v_pk_mul_f32 v[160:161], v[144:145], v[226:227]
	v_pk_mul_f32 v[162:163], v[146:147], v[228:229]
	v_pk_mul_f32 v[144:145], v[144:145], v[218:219]
	v_pk_mul_f32 v[146:147], v[146:147], v[234:235]
	v_pk_fma_f32 v[162:163], v[158:159], v[234:235], v[162:163] neg_lo:[0,0,1] neg_hi:[0,0,1]
	v_pk_fma_f32 v[160:161], v[156:157], v[218:219], v[160:161] neg_lo:[0,0,1] neg_hi:[0,0,1]
	v_pk_fma_f32 v[146:147], v[158:159], v[228:229], v[146:147]
	v_pk_fma_f32 v[144:145], v[156:157], v[226:227], v[144:145]
	s_waitcnt vmcnt(0)
	v_mov_b64_e32 v[156:157], v[240:241]
	v_mov_b64_e32 v[158:159], v[242:243]
	v_mov_b64_e32 v[218:219], v[244:245]
	v_mov_b64_e32 v[220:221], v[246:247]
	s_waitcnt vmcnt(1)
	v_mov_b32_e32 v238, v157
	v_mov_b32_e32 v239, v159
	s_waitcnt vmcnt(0)
	v_mov_b32_e32 v226, v219
	v_mov_b32_e32 v227, v221
	v_pk_mul_f32 v[234:235], v[148:149], v[238:239]
	v_mov_b32_e32 v219, v220
	v_mov_b32_e32 v157, v158
	v_pk_mul_f32 v[228:229], v[150:151], v[226:227]
	v_pk_fma_f32 v[234:235], v[152:153], v[156:157], v[234:235] neg_lo:[0,0,1] neg_hi:[0,0,1]
	v_pk_mul_f32 v[150:151], v[150:151], v[218:219]
	v_pk_mul_f32 v[148:149], v[148:149], v[156:157]
	v_pk_fma_f32 v[236:237], v[154:155], v[218:219], v[228:229] neg_lo:[0,0,1] neg_hi:[0,0,1]
	v_pk_fma_f32 v[150:151], v[154:155], v[226:227], v[150:151]
	v_pk_fma_f32 v[148:149], v[152:153], v[238:239], v[148:149]
	v_mov_b64_e32 v[152:153], v[234:235]
	v_mov_b64_e32 v[156:157], v[160:161]
	v_mov_b64_e32 v[154:155], v[236:237]
	v_mov_b64_e32 v[158:159], v[162:163]

;     __device__ __forceinline__ void operator()(const f32x4 (&acc)[2][2][4][2], const Unit& u, int wr, int wc, int fr, int fq) const {
;     ...
;                     if (lat && (isq || isk)) {
; #pragma unroll
;                         for (int bj = 0; bj < 2; ++bj) {
;                             const int p = bj == 0 ? (t >> 6) : 128 + (t & 63);
;                             const f32x4 cs0 = *(const f32x4*)(ROPE + (p * 16 + 4 * fq) * 2), cs1 = *(const f32x4*)(ROPE + (p * 16 + 4 * fq) * 2 + 4);
;                             const f32x4 cv = {cs0[0], cs0[2], cs1[0], cs1[2]}, sv = {cs0[1], cs0[3], cs1[1], cs1[3]};
;                             const f32x4 a = v[bj][0], bb = v[bj][1];
;                             v[bj][0] = a * cv - bb * sv; v[bj][1] = bb * cv + a * sv;
;                         }
.LBB0_203:
	s_ashr_i32 s30, s50, 1
	v_or_b32_e32 v160, s30, v230
	v_readlane_b32 s30, v254, 41
	v_ashrrev_i32_e32 v161, 31, v160
	v_readlane_b32 s31, v254, 42
	s_nop 1
	v_lshl_add_u64 v[160:161], v[160:161], 2, s[30:31]
	global_load_dwordx4 v[218:221], v[160:161], off
	global_load_dwordx4 v[234:237], v[160:161], off offset:16
	global_load_dwordx4 v[240:243], v[204:205], off
	global_load_dwordx4 v[244:247], v[204:205], off offset:16
	s_waitcnt vmcnt(2)
	v_mov_b32_e32 v226, v219
	v_mov_b32_e32 v227, v221
	v_mov_b32_e32 v228, v235
	v_mov_b32_e32 v229, v237
	v_mov_b32_e32 v235, v236
	v_mov_b32_e32 v219, v220
	v_pk_mul_f32 v[160:161], v[144:145], v[226:227]
	v_pk_mul_f32 v[162:163], v[146:147], v[228:229]
	v_pk_mul_f32 v[144:145], v[144:145], v[218:219]
	v_pk_mul_f32 v[146:147], v[146:147], v[234:235]
	v_pk_fma_f32 v[162:163], v[158:159], v[234:235], v[162:163] neg_lo:[0,0,1] neg_hi:[0,0,1]
	v_pk_fma_f32 v[160:161], v[156:157], v[218:219], v[160:161] neg_lo:[0,0,1] neg_hi:[0,0,1]
	v_pk_fma_f32 v[146:147], v[158:159], v[228:229], v[146:147]
	v_pk_fma_f32 v[144:145], v[156:157], v[226:227], v[144:145]
	s_waitcnt vmcnt(0)
	v_mov_b64_e32 v[156:157], v[240:241]
	v_mov_b64_e32 v[158:159], v[242:243]
	v_mov_b64_e32 v[218:219], v[244:245]
	v_mov_b64_e32 v[220:221], v[246:247]
	s_waitcnt vmcnt(1)
	v_mov_b32_e32 v238, v157
	v_mov_b32_e32 v239, v159
	s_waitcnt vmcnt(0)
	v_mov_b32_e32 v226, v219
	v_mov_b32_e32 v227, v221
	v_pk_mul_f32 v[234:235], v[148:149], v[238:239]
	v_mov_b32_e32 v219, v220
	v_mov_b32_e32 v157, v158
	v_pk_mul_f32 v[228:229], v[150:151], v[226:227]
	v_pk_fma_f32 v[234:235], v[152:153], v[156:157], v[234:235] neg_lo:[0,0,1] neg_hi:[0,0,1]
	v_pk_mul_f32 v[150:151], v[150:151], v[218:219]
	v_pk_mul_f32 v[148:149], v[148:149], v[156:157]
	v_pk_fma_f32 v[236:237], v[154:155], v[218:219], v[228:229] neg_lo:[0,0,1] neg_hi:[0,0,1]
	v_pk_fma_f32 v[150:151], v[154:155], v[226:227], v[150:151]
	v_pk_fma_f32 v[148:149], v[152:153], v[238:239], v[148:149]
	v_mov_b64_e32 v[152:153], v[234:235]
	v_mov_b64_e32 v[156:157], v[160:161]
	v_mov_b64_e32 v[154:155], v[236:237]
	v_mov_b64_e32 v[158:159], v[162:163]
	s_and_b64 vcc, exec, s[14:15]
	s_mov_b64 s[30:31], -1
	s_cbranch_vccz .LBB0_201

;     __device__ __forceinline__ void operator()(const f32x4 (&acc)[2][2][4][2], const Unit& u, int wr, int wc, int fr, int fq) const {
;     ...
;                     if (lat && (isq || isk)) {
; #pragma unroll
;                         for (int bj = 0; bj < 2; ++bj) {
;                             const int p = bj == 0 ? (t >> 6) : 128 + (t & 63);
;                             const f32x4 cs0 = *(const f32x4*)(ROPE + (p * 16 + 4 * fq) * 2), cs1 = *(const f32x4*)(ROPE + (p * 16 + 4 * fq) * 2 + 4);
;                             const f32x4 cv = {cs0[0], cs0[2], cs1[0], cs1[2]}, sv = {cs0[1], cs0[3], cs1[1], cs1[3]};
;                             const f32x4 a = v[bj][0], bb = v[bj][1];
;                             v[bj][0] = a * cv - bb * sv; v[bj][1] = bb * cv + a * sv;
;                         }
.LBB0_215:
	s_ashr_i32 s30, s50, 1
	v_or_b32_e32 v160, s30, v230
	v_readlane_b32 s30, v254, 41
	v_ashrrev_i32_e32 v161, 31, v160
	v_readlane_b32 s31, v254, 42
	s_nop 1
	v_lshl_add_u64 v[160:161], v[160:161], 2, s[30:31]
	global_load_dwordx4 v[218:221], v[160:161], off
	global_load_dwordx4 v[234:237], v[160:161], off offset:16
	global_load_dwordx4 v[240:243], v[206:207], off
	global_load_dwordx4 v[244:247], v[206:207], off offset:16
	s_waitcnt vmcnt(2)
	v_mov_b32_e32 v226, v219
	v_mov_b32_e32 v227, v221
	v_mov_b32_e32 v228, v235
	v_mov_b32_e32 v229, v237
	v_mov_b32_e32 v235, v236
	v_mov_b32_e32 v219, v220
	v_pk_mul_f32 v[160:161], v[144:145], v[226:227]
	v_pk_mul_f32 v[162:163], v[146:147], v[228:229]
	v_pk_mul_f32 v[144:145], v[144:145], v[218:219]
	v_pk_mul_f32 v[146:147], v[146:147], v[234:235]
	v_pk_fma_f32 v[162:163], v[158:159], v[234:235], v[162:163] neg_lo:[0,0,1] neg_hi:[0,0,1]
	v_pk_fma_f32 v[160:161], v[156:157], v[218:219], v[160:161] neg_lo:[0,0,1] neg_hi:[0,0,1]
	v_pk_fma_f32 v[146:147], v[158:159], v[228:229], v[146:147]
	v_pk_fma_f32 v[144:145], v[156:157], v[226:227], v[144:145]
	s_waitcnt vmcnt(0)
	v_mov_b64_e32 v[156:157], v[240:241]
	v_mov_b64_e32 v[158:159], v[242:243]
	v_mov_b64_e32 v[218:219], v[244:245]
	v_mov_b64_e32 v[220:221], v[246:247]
	s_waitcnt vmcnt(1)
	v_mov_b32_e32 v238, v157
	v_mov_b32_e32 v239, v159
	s_waitcnt vmcnt(0)
	v_mov_b32_e32 v226, v219
	v_mov_b32_e32 v227, v221
	v_pk_mul_f32 v[234:235], v[148:149], v[238:239]
	v_mov_b32_e32 v219, v220
	v_mov_b32_e32 v157, v158
	v_pk_mul_f32 v[228:229], v[150:151], v[226:227]
	v_pk_fma_f32 v[234:235], v[152:153], v[156:157], v[234:235] neg_lo:[0,0,1] neg_hi:[0,0,1]
	v_pk_mul_f32 v[150:151], v[150:151], v[218:219]
	v_pk_mul_f32 v[148:149], v[148:149], v[156:157]
	v_pk_fma_f32 v[236:237], v[154:155], v[218:219], v[228:229] neg_lo:[0,0,1] neg_hi:[0,0,1]
	v_pk_fma_f32 v[150:151], v[154:155], v[226:227], v[150:151]
	v_pk_fma_f32 v[148:149], v[152:153], v[238:239], v[148:149]
	v_mov_b64_e32 v[152:153], v[234:235]
	v_mov_b64_e32 v[156:157], v[160:161]
	v_mov_b64_e32 v[154:155], v[236:237]
	v_mov_b64_e32 v[158:159], v[162:163]
	s_and_b64 vcc, exec, s[14:15]
	s_mov_b64 s[30:31], -1
	s_cbranch_vccz .LBB0_213

;     __device__ __forceinline__ void operator()(const f32x4 (&acc)[2][2][4][2], const Unit& u, int wr, int wc, int fr, int fq) const {
;     ...
;                     if (lat && (isq || isk)) {
; #pragma unroll
;                         for (int bj = 0; bj < 2; ++bj) {
;                             const int p = bj == 0 ? (t >> 6) : 128 + (t & 63);
;                             const f32x4 cs0 = *(const f32x4*)(ROPE + (p * 16 + 4 * fq) * 2), cs1 = *(const f32x4*)(ROPE + (p * 16 + 4 * fq) * 2 + 4);
;                             const f32x4 cv = {cs0[0], cs0[2], cs1[0], cs1[2]}, sv = {cs0[1], cs0[3], cs1[1], cs1[3]};
;                             const f32x4 a = v[bj][0], bb = v[bj][1];
;                             v[bj][0] = a * cv - bb * sv; v[bj][1] = bb * cv + a * sv;
;                         }
.LBB0_224:
	s_and_b64 vcc, exec, s[10:11]
	s_addk_i32 s50, 0x80
	s_cbranch_vccnz .LBB0_226
	s_ashr_i32 s30, s50, 1
	v_or_b32_e32 v160, s30, v230
	v_readlane_b32 s30, v254, 41
	v_ashrrev_i32_e32 v161, 31, v160
	v_readlane_b32 s31, v254, 42
	s_nop 1
	v_lshl_add_u64 v[160:161], v[160:161], 2, s[30:31]
	global_load_dwordx4 v[218:221], v[160:161], off
	global_load_dwordx4 v[234:237], v[160:161], off offset:16
	global_load_dwordx4 v[240:243], v[200:201], off
	global_load_dwordx4 v[244:247], v[200:201], off offset:16
	s_waitcnt vmcnt(2)
	v_mov_b32_e32 v214, v219
	v_mov_b32_e32 v215, v221
	v_mov_b32_e32 v226, v235
	v_mov_b32_e32 v227, v237
	v_mov_b32_e32 v235, v236
	v_mov_b32_e32 v219, v220
	v_pk_mul_f32 v[160:161], v[144:145], v[214:215]
	v_pk_mul_f32 v[162:163], v[146:147], v[226:227]
	v_pk_mul_f32 v[144:145], v[144:145], v[218:219]
	v_pk_mul_f32 v[146:147], v[146:147], v[234:235]
	v_pk_fma_f32 v[162:163], v[158:159], v[234:235], v[162:163] neg_lo:[0,0,1] neg_hi:[0,0,1]
	v_pk_fma_f32 v[160:161], v[156:157], v[218:219], v[160:161] neg_lo:[0,0,1] neg_hi:[0,0,1]
	v_pk_fma_f32 v[146:147], v[158:159], v[226:227], v[146:147]
	v_pk_fma_f32 v[144:145], v[156:157], v[214:215], v[144:145]
	s_waitcnt vmcnt(0)
	v_mov_b64_e32 v[156:157], v[240:241]
	v_mov_b64_e32 v[158:159], v[242:243]
	v_mov_b64_e32 v[218:219], v[244:245]
	v_mov_b64_e32 v[220:221], v[246:247]
	s_waitcnt vmcnt(1)
	v_mov_b32_e32 v228, v157
	v_mov_b32_e32 v229, v159
	s_waitcnt vmcnt(0)
	v_mov_b32_e32 v214, v219
	v_mov_b32_e32 v215, v221
	v_pk_mul_f32 v[234:235], v[148:149], v[228:229]
	v_mov_b32_e32 v219, v220
	v_mov_b32_e32 v157, v158
	v_pk_mul_f32 v[226:227], v[150:151], v[214:215]
	v_pk_fma_f32 v[234:235], v[152:153], v[156:157], v[234:235] neg_lo:[0,0,1] neg_hi:[0,0,1]
	v_pk_mul_f32 v[150:151], v[150:151], v[218:219]
	v_pk_mul_f32 v[148:149], v[148:149], v[156:157]
	v_pk_fma_f32 v[236:237], v[154:155], v[218:219], v[226:227] neg_lo:[0,0,1] neg_hi:[0,0,1]
	v_pk_fma_f32 v[150:151], v[154:155], v[214:215], v[150:151]
	v_pk_fma_f32 v[148:149], v[152:153], v[228:229], v[148:149]
	v_mov_b64_e32 v[152:153], v[234:235]
	v_mov_b64_e32 v[156:157], v[160:161]
	v_mov_b64_e32 v[154:155], v[236:237]
	v_mov_b64_e32 v[158:159], v[162:163]

;     __device__ __forceinline__ void operator()(const f32x4 (&acc)[2][2][4][2], const Unit& u, int wr, int wc, int fr, int fq) const {
;     ...
;                     if (lat && (isq || isk)) {
; #pragma unroll
;                         for (int bj = 0; bj < 2; ++bj) {
;                             const int p = bj == 0 ? (t >> 6) : 128 + (t & 63);
;                             const f32x4 cs0 = *(const f32x4*)(ROPE + (p * 16 + 4 * fq) * 2), cs1 = *(const f32x4*)(ROPE + (p * 16 + 4 * fq) * 2 + 4);
;                             const f32x4 cv = {cs0[0], cs0[2], cs1[0], cs1[2]}, sv = {cs0[1], cs0[3], cs1[1], cs1[3]};
;                             const f32x4 a = v[bj][0], bb = v[bj][1];
;                             v[bj][0] = a * cv - bb * sv; v[bj][1] = bb * cv + a * sv;
;                         }
.LBB0_239:
	s_ashr_i32 s30, s50, 1
	v_or_b32_e32 v160, s30, v230
	v_readlane_b32 s30, v254, 41
	v_ashrrev_i32_e32 v161, 31, v160
	v_readlane_b32 s31, v254, 42
	s_nop 1
	v_lshl_add_u64 v[160:161], v[160:161], 2, s[30:31]
	global_load_dwordx4 v[218:221], v[160:161], off
	global_load_dwordx4 v[234:237], v[160:161], off offset:16
	global_load_dwordx4 v[240:243], v[202:203], off
	global_load_dwordx4 v[244:247], v[202:203], off offset:16
	s_waitcnt vmcnt(2)
	v_mov_b32_e32 v226, v219
	v_mov_b32_e32 v227, v221
	v_mov_b32_e32 v228, v235
	v_mov_b32_e32 v229, v237
	v_mov_b32_e32 v235, v236
	v_mov_b32_e32 v219, v220
	v_pk_mul_f32 v[160:161], v[144:145], v[226:227]
	v_pk_mul_f32 v[162:163], v[146:147], v[228:229]
	v_pk_mul_f32 v[144:145], v[144:145], v[218:219]
	v_pk_mul_f32 v[146:147], v[146:147], v[234:235]
	v_pk_fma_f32 v[162:163], v[158:159], v[234:235], v[162:163] neg_lo:[0,0,1] neg_hi:[0,0,1]
	v_pk_fma_f32 v[160:161], v[156:157], v[218:219], v[160:161] neg_lo:[0,0,1] neg_hi:[0,0,1]
	v_pk_fma_f32 v[146:147], v[158:159], v[228:229], v[146:147]
	v_pk_fma_f32 v[144:145], v[156:157], v[226:227], v[144:145]
	s_waitcnt vmcnt(0)
	v_mov_b64_e32 v[156:157], v[240:241]
	v_mov_b64_e32 v[158:159], v[242:243]
	v_mov_b64_e32 v[218:219], v[244:245]
	v_mov_b64_e32 v[220:221], v[246:247]
	s_waitcnt vmcnt(1)
	v_mov_b32_e32 v238, v157
	v_mov_b32_e32 v239, v159
	s_waitcnt vmcnt(0)
	v_mov_b32_e32 v226, v219
	v_mov_b32_e32 v227, v221
	v_pk_mul_f32 v[234:235], v[148:149], v[238:239]
	v_mov_b32_e32 v219, v220
	v_mov_b32_e32 v157, v158
	v_pk_mul_f32 v[228:229], v[150:151], v[226:227]
	v_pk_fma_f32 v[234:235], v[152:153], v[156:157], v[234:235] neg_lo:[0,0,1] neg_hi:[0,0,1]
	v_pk_mul_f32 v[150:151], v[150:151], v[218:219]
	v_pk_mul_f32 v[148:149], v[148:149], v[156:157]
	v_pk_fma_f32 v[236:237], v[154:155], v[218:219], v[228:229] neg_lo:[0,0,1] neg_hi:[0,0,1]
	v_pk_fma_f32 v[150:151], v[154:155], v[226:227], v[150:151]
	v_pk_fma_f32 v[148:149], v[152:153], v[238:239], v[148:149]
	v_mov_b64_e32 v[152:153], v[234:235]
	v_mov_b64_e32 v[156:157], v[160:161]
	v_mov_b64_e32 v[154:155], v[236:237]
	v_mov_b64_e32 v[158:159], v[162:163]
	s_and_b64 vcc, exec, s[14:15]
	s_mov_b64 s[30:31], -1
	s_cbranch_vccz .LBB0_237

;     __device__ __forceinline__ void operator()(const f32x4 (&acc)[2][2][4][2], const Unit& u, int wr, int wc, int fr, int fq) const {
;     ...
;                     if (lat && (isq || isk)) {
; #pragma unroll
;                         for (int bj = 0; bj < 2; ++bj) {
;                             const int p = bj == 0 ? (t >> 6) : 128 + (t & 63);
;                             const f32x4 cs0 = *(const f32x4*)(ROPE + (p * 16 + 4 * fq) * 2), cs1 = *(const f32x4*)(ROPE + (p * 16 + 4 * fq) * 2 + 4);
;                             const f32x4 cv = {cs0[0], cs0[2], cs1[0], cs1[2]}, sv = {cs0[1], cs0[3], cs1[1], cs1[3]};
;                             const f32x4 a = v[bj][0], bb = v[bj][1];
;                             v[bj][0] = a * cv - bb * sv; v[bj][1] = bb * cv + a * sv;
;                         }
.LBB0_263:
	s_ashr_i32 s8, s50, 1
	s_waitcnt vmcnt(0)
	v_or_b32_e32 v128, s8, v230
	v_readlane_b32 s8, v254, 41
	v_ashrrev_i32_e32 v129, 31, v128
	v_readlane_b32 s9, v254, 42
	s_nop 1
	v_lshl_add_u64 v[128:129], v[128:129], 2, s[8:9]
	global_load_dwordx4 v[132:135], v[128:129], off
	global_load_dwordx4 v[136:139], v[128:129], off offset:16
	global_load_dwordx4 v[240:243], v[206:207], off
	global_load_dwordx4 v[244:247], v[206:207], off offset:16
	s_waitcnt vmcnt(3)
	v_mov_b32_e32 v140, v133
	v_mov_b32_e32 v141, v135
	v_pk_mul_f32 v[128:129], v[144:145], v[140:141]
	s_waitcnt vmcnt(2)
	v_mov_b32_e32 v142, v137
	v_mov_b32_e32 v143, v139
	v_mov_b32_e32 v137, v138
	v_mov_b32_e32 v133, v134
	v_pk_mul_f32 v[130:131], v[146:147], v[142:143]
	v_pk_fma_f32 v[128:129], v[156:157], v[132:133], v[128:129] neg_lo:[0,0,1] neg_hi:[0,0,1]
	v_pk_mul_f32 v[132:133], v[144:145], v[132:133]
	v_pk_mul_f32 v[134:135], v[146:147], v[136:137]
	v_pk_fma_f32 v[130:131], v[158:159], v[136:137], v[130:131] neg_lo:[0,0,1] neg_hi:[0,0,1]
	v_pk_fma_f32 v[146:147], v[158:159], v[142:143], v[134:135]
	v_pk_fma_f32 v[144:145], v[156:157], v[140:141], v[132:133]
	s_waitcnt vmcnt(0)
	v_mov_b64_e32 v[132:133], v[240:241]
	v_mov_b64_e32 v[134:135], v[242:243]
	v_mov_b64_e32 v[136:137], v[244:245]
	v_mov_b64_e32 v[138:139], v[246:247]
	s_waitcnt vmcnt(1)
	v_mov_b32_e32 v156, v133
	s_waitcnt vmcnt(0)
	v_mov_b32_e32 v142, v137
	v_mov_b32_e32 v143, v139
	v_mov_b32_e32 v157, v135
	v_pk_mul_f32 v[140:141], v[150:151], v[142:143]
	v_pk_mul_f32 v[158:159], v[148:149], v[156:157]
	v_mov_b32_e32 v137, v138
	v_mov_b32_e32 v133, v134
	v_pk_fma_f32 v[140:141], v[154:155], v[136:137], v[140:141] neg_lo:[0,0,1] neg_hi:[0,0,1]
	v_pk_fma_f32 v[138:139], v[152:153], v[132:133], v[158:159] neg_lo:[0,0,1] neg_hi:[0,0,1]
	v_pk_mul_f32 v[134:135], v[150:151], v[136:137]
	v_pk_mul_f32 v[132:133], v[148:149], v[132:133]
	v_pk_fma_f32 v[150:151], v[154:155], v[142:143], v[134:135]
	v_pk_fma_f32 v[148:149], v[152:153], v[156:157], v[132:133]
	v_mov_b64_e32 v[154:155], v[140:141]
	v_mov_b64_e32 v[158:159], v[130:131]
	v_mov_b64_e32 v[152:153], v[138:139]
	v_mov_b64_e32 v[156:157], v[128:129]
	s_and_b64 vcc, exec, s[14:15]
	s_mov_b64 s[8:9], -1
	s_cbranch_vccz .LBB0_261
